# mix_out: idle waves 4-7 touch the next item's chunk states during the attention stage so the next out_write's loads hit L2
# speedup vs baseline: 1.0169x; 1.0031x over previous
.Lspw_0:
	s_and_b64 vcc, exec, s[62:63]
	s_cbranch_vccnz .LBB0_855
	v_readlane_b32 s0, v253, 40
	v_readlane_b32 s1, v253, 41
	s_lshl_b32 s22, s75, 5
	s_add_i32 s22, s22, s74
	s_mul_i32 s22, s22, 0x120
	s_mul_i32 s60, s77, 0x90
	s_add_i32 s22, s22, s60
	s_add_i32 s22, s22, s76
	s_mul_i32 s22, s22, 0x2400
	s_add_u32 s0, s0, s22
	s_addc_u32 s1, s1, 0
	v_subrev_u32_e32 v124, 0x100, v224
	v_mul_u32_u24_e32 v126, 0x1c72, v124
	v_lshrrev_b32_e32 v126, 20, v126
	v_mul_u32_u24_e32 v126, 0x4ec00, v126
	v_lshl_add_u32 v126, v124, 6, v126
	global_load_dword v127, v126, s[0:1]
	v_add_u32_e32 v125, 0x100, v124
	v_mul_u32_u24_e32 v126, 0x1c72, v125
	v_lshrrev_b32_e32 v126, 20, v126
	v_mul_u32_u24_e32 v126, 0x4ec00, v126
	v_lshl_add_u32 v126, v125, 6, v126
	global_load_dword v128, v126, s[0:1]
	v_add_u32_e32 v125, 0x200, v124
	v_min_u32_e32 v125, 0x23f, v125
	v_mul_u32_u24_e32 v126, 0x1c72, v125
	v_lshrrev_b32_e32 v126, 20, v126
	v_mul_u32_u24_e32 v126, 0x4ec00, v126
	v_lshl_add_u32 v126, v125, 6, v126
	global_load_dword v129, v126, s[0:1]
	s_waitcnt vmcnt(0)
